# v11 plus: gate/up K-loop LDS-DMA loads use the saddr form (16 VALU 64-bit address adds per iteration removed from the load segments)
# speedup vs baseline: 1.0164x; 1.0164x over previous
; #define PG8_STAGE(bufoff, gbase, voff) do { _Pragma("unroll") for (int _i = 0; _i < 2; ++_i) \
;         __builtin_amdgcn_global_load_lds((const unsigned*)((const char*)(gbase) + (voff)[_i]), (LAS unsigned*)(lds + (bufoff) + ldsw + _i * 8192), 16, 0, 0); } while (0)
; #define PG8_LDA(dst, b, h) do { _Pragma("unroll") for (int m = 0; m < 4; ++m) _Pragma("unroll") for (int k = 0; k < 2; ++k) dst[m][k] = *(const LAS bf16x8*)(lds + PG8_SA(b, h) + aoff + m * 2048 + k * 1024); } while (0)
; #define PG8_LDB(dst, b, h) do { _Pragma("unroll") for (int n = 0; n < 2; ++n) _Pragma("unroll") for (int k = 0; k < 2; ++k) dst[n][k] = *(const LAS bf16x8*)(lds + PG8_SB(b, h) + boff + n * 2048 + k * 1024); } while (0)
; #define PG8_MMA(ai, bj, At, Bt) do { __builtin_amdgcn_s_setprio(1); _Pragma("unroll") for (int m = 0; m < 4; ++m) _Pragma("unroll") for (int n = 0; n < 2; ++n) _Pragma("unroll") for (int k = 0; k < 2; ++k) \
;         acc[ai][bj][m][n] = __builtin_amdgcn_mfma_f32_16x16x32_bf16(Bt[n][k], At[m][k], acc[ai][bj][m][n], 0, 0, 0); __builtin_amdgcn_s_setprio(0); } while (0)
; #define PG8_WAIT_V(n) asm volatile("s_waitcnt vmcnt(" #n ")" ::: "memory")
; #define PG8_WAIT_L(n) asm volatile("s_waitcnt lgkmcnt(" #n ")" ::: "memory")
; #define PG8_BAR __builtin_amdgcn_s_barrier()
; #define PG8_SCHED __builtin_amdgcn_sched_barrier(0)
; template <class Epi, class Sched>
; __device__ __forceinline__ void gemm_phase(LAS unsigned char* lds, const Gemm g, const Sched& S, const Epi& E) {
;     ...
;             PG8_LDB(B0, 0, 0); PG8_SCHED; PG8_LDA(At, 0, 0); PG8_STAGE(PG8_SA(1, 1), a1 + hstep, voffA);
;             PG8_WAIT_L(8); PG8_BAR; PG8_WAIT_L(0); PG8_MMA(0, 0, At, B0); PG8_BAR; PG8_SCHED;
;             PG8_LDB(B1, 0, 1); PG8_STAGE(PG8_SB(0, 0), b2, voffB);
;             PG8_BAR; PG8_WAIT_L(0); PG8_MMA(0, 1, At, B1); PG8_BAR;
;             PG8_LDA(At, 0, 1); PG8_STAGE(PG8_SA(0, 0), a2, voffA);
;             PG8_BAR; PG8_WAIT_L(0); PG8_MMA(1, 0, At, B0); PG8_BAR; PG8_SCHED;
;             PG8_STAGE(PG8_SB(0, 1), b2 + hstep, voffB);
;             PG8_WAIT_V(6); PG8_BAR; PG8_MMA(1, 1, At, B1); PG8_BAR;
.LBB0_213:
	s_add_u32 s20, s16, 0xfff80080
	s_addc_u32 s21, s17, -1
	s_add_i32 s45, 0, 0x10000
	v_add_u32_e32 v138, s45, v141
	ds_read_b128 v[144:147], v138
	ds_read_b128 v[160:163], v138 offset:1024
	ds_read_b128 v[164:167], v138 offset:2048
	ds_read_b128 v[168:171], v138 offset:3072
	s_cmp_eq_u32 s44, 28
	s_cselect_b32 s23, s11, s21
	s_cselect_b32 s22, s40, s20
	s_cselect_b32 s21, s7, s43
	s_cselect_b32 s20, s41, s42
	s_add_i32 m0, s30, 0xc000
	ds_read_b128 v[172:175], v143
	ds_read_b128 v[200:203], v143 offset:1024
	ds_read_b128 v[204:207], v143 offset:2048
	ds_read_b128 v[208:211], v143 offset:3072
	ds_read_b128 v[212:215], v143 offset:4096
	ds_read_b128 v[216:219], v143 offset:5120
	ds_read_b128 v[220:223], v143 offset:6144
	ds_read_b128 v[224:227], v143 offset:7168
	global_load_lds_dwordx4 v134, s[16:17]
	s_add_i32 m0, s30, 0xe000
	s_nop 0
	global_load_lds_dwordx4 v136, s[16:17]
	s_waitcnt lgkmcnt(8)
	s_barrier
	s_waitcnt lgkmcnt(0)
	s_waitcnt lgkmcnt(0)
	v_mfma_f32_16x16x32_bf16 v[124:127], v[144:147], v[172:175], v[124:127]
	v_mfma_f32_16x16x32_bf16 v[116:119], v[164:167], v[172:175], v[116:119]
	v_mfma_f32_16x16x32_bf16 v[108:111], v[144:147], v[204:207], v[108:111]
	v_mfma_f32_16x16x32_bf16 v[100:103], v[164:167], v[204:207], v[100:103]
	v_mfma_f32_16x16x32_bf16 v[92:95], v[144:147], v[212:215], v[92:95]
	v_mfma_f32_16x16x32_bf16 v[84:87], v[164:167], v[212:215], v[84:87]
	v_mfma_f32_16x16x32_bf16 v[76:79], v[144:147], v[220:223], v[76:79]
	v_mfma_f32_16x16x32_bf16 v[68:71], v[164:167], v[220:223], v[68:71]
	v_mfma_f32_16x16x32_bf16 v[124:127], v[160:163], v[200:203], v[124:127]
	v_mfma_f32_16x16x32_bf16 v[116:119], v[168:171], v[200:203], v[116:119]
	v_mfma_f32_16x16x32_bf16 v[108:111], v[160:163], v[208:211], v[108:111]
	v_mfma_f32_16x16x32_bf16 v[100:103], v[168:171], v[208:211], v[100:103]
	v_mfma_f32_16x16x32_bf16 v[92:95], v[160:163], v[216:219], v[92:95]
	v_mfma_f32_16x16x32_bf16 v[84:87], v[168:171], v[216:219], v[84:87]
	v_mfma_f32_16x16x32_bf16 v[76:79], v[160:163], v[224:227], v[76:79]
	v_mfma_f32_16x16x32_bf16 v[68:71], v[168:171], v[224:227], v[68:71]
	s_barrier
	s_add_i32 s48, 0, 0x14000
	v_add_u32_e32 v138, s48, v141
	s_add_i32 s45, s45, s29
	ds_read_b128 v[228:231], v138
	ds_read_b128 v[232:235], v138 offset:1024
	ds_read_b128 v[236:239], v138 offset:2048
	ds_read_b128 v[240:243], v138 offset:3072
	s_add_u32 s84, s20, 0x80
	s_addc_u32 s85, s21, 0
	s_mov_b32 m0, s45
	s_nop 0
	global_load_lds_dwordx4 v148, s[20:21]
	s_add_i32 m0, s45, 0x2000
	s_nop 0
	global_load_lds_dwordx4 v128, s[20:21]
	s_barrier
	s_waitcnt lgkmcnt(0)
	s_waitcnt lgkmcnt(0)
	v_mfma_f32_16x16x32_bf16 v[120:123], v[228:231], v[172:175], v[120:123]
	v_mfma_f32_16x16x32_bf16 v[112:115], v[236:239], v[172:175], v[112:115]
	v_mfma_f32_16x16x32_bf16 v[104:107], v[228:231], v[204:207], v[104:107]
	v_mfma_f32_16x16x32_bf16 v[96:99], v[236:239], v[204:207], v[96:99]
	v_mfma_f32_16x16x32_bf16 v[88:91], v[228:231], v[212:215], v[88:91]
	v_mfma_f32_16x16x32_bf16 v[80:83], v[236:239], v[212:215], v[80:83]
	v_mfma_f32_16x16x32_bf16 v[72:75], v[228:231], v[220:223], v[72:75]
	v_mfma_f32_16x16x32_bf16 v[64:67], v[236:239], v[220:223], v[64:67]
	v_mfma_f32_16x16x32_bf16 v[120:123], v[232:235], v[200:203], v[120:123]
	v_mfma_f32_16x16x32_bf16 v[112:115], v[240:243], v[200:203], v[112:115]
	v_mfma_f32_16x16x32_bf16 v[104:107], v[232:235], v[208:211], v[104:107]
	v_mfma_f32_16x16x32_bf16 v[96:99], v[240:243], v[208:211], v[96:99]
	v_mfma_f32_16x16x32_bf16 v[88:91], v[232:235], v[216:219], v[88:91]
	v_mfma_f32_16x16x32_bf16 v[80:83], v[240:243], v[216:219], v[80:83]
	v_mfma_f32_16x16x32_bf16 v[72:75], v[232:235], v[224:227], v[72:75]
	v_mfma_f32_16x16x32_bf16 v[64:67], v[240:243], v[224:227], v[64:67]
	s_mov_b32 m0, s30
	s_add_u32 s86, s22, 0x80
	s_addc_u32 s87, s23, 0
	s_barrier
	ds_read_b128 v[172:175], v143 offset:16384
	ds_read_b128 v[200:203], v143 offset:17408
	ds_read_b128 v[204:207], v143 offset:18432
	ds_read_b128 v[208:211], v143 offset:19456
	ds_read_b128 v[212:215], v143 offset:20480
	ds_read_b128 v[216:219], v143 offset:21504
	ds_read_b128 v[220:223], v143 offset:22528
	ds_read_b128 v[224:227], v143 offset:23552
	global_load_lds_dwordx4 v132, s[22:23]
	s_mov_b32 m0, s31
	s_nop 0
	global_load_lds_dwordx4 v130, s[22:23]
	s_barrier
	s_waitcnt lgkmcnt(0)
	s_waitcnt lgkmcnt(0)
	v_mfma_f32_16x16x32_bf16 v[60:63], v[144:147], v[172:175], v[60:63]
	v_mfma_f32_16x16x32_bf16 v[52:55], v[164:167], v[172:175], v[52:55]
	v_mfma_f32_16x16x32_bf16 v[44:47], v[144:147], v[204:207], v[44:47]
	v_mfma_f32_16x16x32_bf16 v[36:39], v[164:167], v[204:207], v[36:39]
	v_mfma_f32_16x16x32_bf16 v[28:31], v[144:147], v[212:215], v[28:31]
	v_mfma_f32_16x16x32_bf16 v[20:23], v[164:167], v[212:215], v[20:23]
	v_mfma_f32_16x16x32_bf16 v[12:15], v[144:147], v[220:223], v[12:15]
	v_mfma_f32_16x16x32_bf16 v[4:7], v[164:167], v[220:223], v[4:7]
	v_mfma_f32_16x16x32_bf16 v[60:63], v[160:163], v[200:203], v[60:63]
	v_mfma_f32_16x16x32_bf16 v[52:55], v[168:171], v[200:203], v[52:55]
	v_mfma_f32_16x16x32_bf16 v[44:47], v[160:163], v[208:211], v[44:47]
	v_mfma_f32_16x16x32_bf16 v[36:39], v[168:171], v[208:211], v[36:39]
	v_mfma_f32_16x16x32_bf16 v[28:31], v[160:163], v[216:219], v[28:31]
	v_mfma_f32_16x16x32_bf16 v[20:23], v[168:171], v[216:219], v[20:23]
	v_mfma_f32_16x16x32_bf16 v[12:15], v[160:163], v[224:227], v[12:15]
	v_mfma_f32_16x16x32_bf16 v[4:7], v[168:171], v[224:227], v[4:7]
	s_barrier
	s_add_u32 s46, s20, 0x80000
	s_addc_u32 s47, s21, 0
	s_add_i32 s45, s48, s29
	s_mov_b32 m0, s45
	s_nop 0
	global_load_lds_dwordx4 v148, s[46:47]
	s_add_i32 m0, s45, 0x2000
	s_nop 0
	global_load_lds_dwordx4 v128, s[46:47]
	s_waitcnt vmcnt(6)
	s_barrier
; #define PG8_STAGE(bufoff, gbase, voff) do { _Pragma("unroll") for (int _i = 0; _i < 2; ++_i) \
;         __builtin_amdgcn_global_load_lds((const unsigned*)((const char*)(gbase) + (voff)[_i]), (LAS unsigned*)(lds + (bufoff) + ldsw + _i * 8192), 16, 0, 0); } while (0)
; #define PG8_LDA(dst, b, h) do { _Pragma("unroll") for (int m = 0; m < 4; ++m) _Pragma("unroll") for (int k = 0; k < 2; ++k) dst[m][k] = *(const LAS bf16x8*)(lds + PG8_SA(b, h) + aoff + m * 2048 + k * 1024); } while (0)
; #define PG8_LDB(dst, b, h) do { _Pragma("unroll") for (int n = 0; n < 2; ++n) _Pragma("unroll") for (int k = 0; k < 2; ++k) dst[n][k] = *(const LAS bf16x8*)(lds + PG8_SB(b, h) + boff + n * 2048 + k * 1024); } while (0)
; #define PG8_MMA(ai, bj, At, Bt) do { __builtin_amdgcn_s_setprio(1); _Pragma("unroll") for (int m = 0; m < 4; ++m) _Pragma("unroll") for (int n = 0; n < 2; ++n) _Pragma("unroll") for (int k = 0; k < 2; ++k) \
;         acc[ai][bj][m][n] = __builtin_amdgcn_mfma_f32_16x16x32_bf16(Bt[n][k], At[m][k], acc[ai][bj][m][n], 0, 0, 0); __builtin_amdgcn_s_setprio(0); } while (0)
; #define PG8_WAIT_V(n) asm volatile("s_waitcnt vmcnt(" #n ")" ::: "memory")
; #define PG8_WAIT_L(n) asm volatile("s_waitcnt lgkmcnt(" #n ")" ::: "memory")
; #define PG8_BAR __builtin_amdgcn_s_barrier()
; #define PG8_SCHED __builtin_amdgcn_sched_barrier(0)
; template <class Epi, class Sched>
; __device__ __forceinline__ void gemm_phase(LAS unsigned char* lds, const Gemm g, const Sched& S, const Epi& E) {
;     ...
;             PG8_WAIT_V(6); PG8_BAR; PG8_MMA(1, 1, At, B1); PG8_BAR;
;             PG8_LDB(B0, 1, 0); PG8_SCHED; PG8_LDA(At, 1, 0); PG8_STAGE(PG8_SA(0, 1), a2 + hstep, voffA);
;             PG8_WAIT_L(8); PG8_BAR; PG8_WAIT_L(0); PG8_MMA(0, 0, At, B0); PG8_BAR; PG8_SCHED;
;             PG8_LDB(B1, 1, 1); PG8_STAGE(PG8_SB(1, 0), b3, voffB);
;             PG8_BAR; PG8_WAIT_L(0); PG8_MMA(0, 1, At, B1); PG8_BAR;
;             PG8_LDA(At, 1, 1); PG8_STAGE(PG8_SA(1, 0), a3, voffA);
;             PG8_BAR; PG8_WAIT_L(0); PG8_MMA(1, 0, At, B0); PG8_BAR; PG8_SCHED;
	v_mfma_f32_16x16x32_bf16 v[56:59], v[228:231], v[172:175], v[56:59]
	v_mfma_f32_16x16x32_bf16 v[48:51], v[236:239], v[172:175], v[48:51]
	v_mfma_f32_16x16x32_bf16 v[40:43], v[228:231], v[204:207], v[40:43]
	v_mfma_f32_16x16x32_bf16 v[32:35], v[236:239], v[204:207], v[32:35]
	v_mfma_f32_16x16x32_bf16 v[24:27], v[228:231], v[212:215], v[24:27]
	v_mfma_f32_16x16x32_bf16 v[16:19], v[236:239], v[212:215], v[16:19]
	v_mfma_f32_16x16x32_bf16 v[8:11], v[228:231], v[220:223], v[8:11]
	v_mfma_f32_16x16x32_bf16 v[0:3], v[236:239], v[220:223], v[0:3]
	v_mfma_f32_16x16x32_bf16 v[56:59], v[232:235], v[200:203], v[56:59]
	v_mfma_f32_16x16x32_bf16 v[48:51], v[240:243], v[200:203], v[48:51]
	v_mfma_f32_16x16x32_bf16 v[40:43], v[232:235], v[208:211], v[40:43]
	v_mfma_f32_16x16x32_bf16 v[32:35], v[240:243], v[208:211], v[32:35]
	v_mfma_f32_16x16x32_bf16 v[24:27], v[232:235], v[216:219], v[24:27]
	v_mfma_f32_16x16x32_bf16 v[16:19], v[240:243], v[216:219], v[16:19]
	v_mfma_f32_16x16x32_bf16 v[8:11], v[232:235], v[224:227], v[8:11]
	v_mfma_f32_16x16x32_bf16 v[0:3], v[240:243], v[224:227], v[0:3]
	s_add_i32 s45, 0, 0x18000
	v_add_u32_e32 v168, s45, v141
	s_barrier
	ds_read_b128 v[144:147], v168
	ds_read_b128 v[160:163], v168 offset:1024
	ds_read_b128 v[164:167], v168 offset:2048
	ds_read_b128 v[168:171], v168 offset:3072
	s_add_u32 s22, s22, 0x80000
	s_addc_u32 s23, s23, 0
	s_mov_b32 m0, s33
	ds_read_b128 v[172:175], v143 offset:32768
	ds_read_b128 v[200:203], v143 offset:33792
	ds_read_b128 v[204:207], v143 offset:34816
	ds_read_b128 v[208:211], v143 offset:35840
	ds_read_b128 v[212:215], v143 offset:36864
	ds_read_b128 v[216:219], v143 offset:37888
	ds_read_b128 v[220:223], v143 offset:38912
	ds_read_b128 v[224:227], v143 offset:39936
	global_load_lds_dwordx4 v132, s[22:23]
	s_mov_b32 m0, s34
	s_nop 0
	global_load_lds_dwordx4 v130, s[22:23]
	s_waitcnt lgkmcnt(8)
	s_barrier
	s_waitcnt lgkmcnt(0)
	s_waitcnt lgkmcnt(0)
	v_mfma_f32_16x16x32_bf16 v[124:127], v[144:147], v[172:175], v[124:127]
	v_mfma_f32_16x16x32_bf16 v[116:119], v[164:167], v[172:175], v[116:119]
	v_mfma_f32_16x16x32_bf16 v[108:111], v[144:147], v[204:207], v[108:111]
	v_mfma_f32_16x16x32_bf16 v[100:103], v[164:167], v[204:207], v[100:103]
	v_mfma_f32_16x16x32_bf16 v[92:95], v[144:147], v[212:215], v[92:95]
	v_mfma_f32_16x16x32_bf16 v[84:87], v[164:167], v[212:215], v[84:87]
	v_mfma_f32_16x16x32_bf16 v[76:79], v[144:147], v[220:223], v[76:79]
	v_mfma_f32_16x16x32_bf16 v[68:71], v[164:167], v[220:223], v[68:71]
	v_mfma_f32_16x16x32_bf16 v[124:127], v[160:163], v[200:203], v[124:127]
	v_mfma_f32_16x16x32_bf16 v[116:119], v[168:171], v[200:203], v[116:119]
	v_mfma_f32_16x16x32_bf16 v[108:111], v[160:163], v[208:211], v[108:111]
	v_mfma_f32_16x16x32_bf16 v[100:103], v[168:171], v[208:211], v[100:103]
	v_mfma_f32_16x16x32_bf16 v[92:95], v[160:163], v[216:219], v[92:95]
	v_mfma_f32_16x16x32_bf16 v[84:87], v[168:171], v[216:219], v[84:87]
	v_mfma_f32_16x16x32_bf16 v[76:79], v[160:163], v[224:227], v[76:79]
	v_mfma_f32_16x16x32_bf16 v[68:71], v[168:171], v[224:227], v[68:71]
	s_barrier
	s_add_i32 s22, 0, 0x1c000
	s_add_i32 s23, s45, s29
	v_add_u32_e32 v188, s22, v141
	s_mov_b32 m0, s23
	ds_read_b128 v[228:231], v188
	ds_read_b128 v[232:235], v188 offset:1024
	ds_read_b128 v[236:239], v188 offset:2048
	ds_read_b128 v[240:243], v188 offset:3072
	global_load_lds_dwordx4 v148, s[84:85]
	s_add_i32 m0, s23, 0x2000
	s_nop 0
	global_load_lds_dwordx4 v128, s[84:85]
	s_barrier
	s_waitcnt lgkmcnt(0)
	s_waitcnt lgkmcnt(0)
	v_mfma_f32_16x16x32_bf16 v[120:123], v[228:231], v[172:175], v[120:123]
	v_mfma_f32_16x16x32_bf16 v[112:115], v[236:239], v[172:175], v[112:115]
	v_mfma_f32_16x16x32_bf16 v[104:107], v[228:231], v[204:207], v[104:107]
	v_mfma_f32_16x16x32_bf16 v[96:99], v[236:239], v[204:207], v[96:99]
	v_mfma_f32_16x16x32_bf16 v[88:91], v[228:231], v[212:215], v[88:91]
	v_mfma_f32_16x16x32_bf16 v[80:83], v[236:239], v[212:215], v[80:83]
	v_mfma_f32_16x16x32_bf16 v[72:75], v[228:231], v[220:223], v[72:75]
	v_mfma_f32_16x16x32_bf16 v[64:67], v[236:239], v[220:223], v[64:67]
	v_mfma_f32_16x16x32_bf16 v[120:123], v[232:235], v[200:203], v[120:123]
	v_mfma_f32_16x16x32_bf16 v[112:115], v[240:243], v[200:203], v[112:115]
	v_mfma_f32_16x16x32_bf16 v[104:107], v[232:235], v[208:211], v[104:107]
	v_mfma_f32_16x16x32_bf16 v[96:99], v[240:243], v[208:211], v[96:99]
	v_mfma_f32_16x16x32_bf16 v[88:91], v[232:235], v[216:219], v[88:91]
	v_mfma_f32_16x16x32_bf16 v[80:83], v[240:243], v[216:219], v[80:83]
	v_mfma_f32_16x16x32_bf16 v[72:75], v[232:235], v[224:227], v[72:75]
	v_mfma_f32_16x16x32_bf16 v[64:67], v[240:243], v[224:227], v[64:67]
	s_mov_b32 m0, s35
	s_barrier
	ds_read_b128 v[172:175], v143 offset:49152
	ds_read_b128 v[200:203], v143 offset:50176
	ds_read_b128 v[204:207], v143 offset:51200
	ds_read_b128 v[208:211], v143 offset:52224
	ds_read_b128 v[212:215], v143 offset:53248
	ds_read_b128 v[216:219], v143 offset:54272
	ds_read_b128 v[220:223], v143 offset:55296
	ds_read_b128 v[224:227], v143 offset:56320
	global_load_lds_dwordx4 v132, s[86:87]
	s_mov_b32 m0, s36
	s_nop 0
	global_load_lds_dwordx4 v130, s[86:87]
	s_barrier
; __device__ __forceinline__ unsigned cvt_pk_bf16(float lo, float hi) { unsigned r; asm("v_cvt_pk_bf16_f32 %0, %1, %2" : "=v"(r) : "v"(lo), "v"(hi)); return r; }
; #define PG8_STAGE(bufoff, gbase, voff) do { _Pragma("unroll") for (int _i = 0; _i < 2; ++_i) \
;         __builtin_amdgcn_global_load_lds((const unsigned*)((const char*)(gbase) + (voff)[_i]), (LAS unsigned*)(lds + (bufoff) + ldsw + _i * 8192), 16, 0, 0); } while (0)
; #define PG8_MMA(ai, bj, At, Bt) do { __builtin_amdgcn_s_setprio(1); _Pragma("unroll") for (int m = 0; m < 4; ++m) _Pragma("unroll") for (int n = 0; n < 2; ++n) _Pragma("unroll") for (int k = 0; k < 2; ++k) \
;         acc[ai][bj][m][n] = __builtin_amdgcn_mfma_f32_16x16x32_bf16(Bt[n][k], At[m][k], acc[ai][bj][m][n], 0, 0, 0); __builtin_amdgcn_s_setprio(0); } while (0)
; #define PG8_WAIT_V(n) asm volatile("s_waitcnt vmcnt(" #n ")" ::: "memory")
; #define PG8_WAIT_L(n) asm volatile("s_waitcnt lgkmcnt(" #n ")" ::: "memory")
; #define PG8_BAR __builtin_amdgcn_s_barrier()
;     __device__ __forceinline__ void operator()(const f32x4 (&acc)[2][2][4][2], const Unit& u, int wr, int wc, int fr, int fq) const {
;         const int row0 = u.pm * BM + wr * 64 + fr, col0 = u.pn * HALF + wc * 32 + 8 * fq;
; #pragma unroll
;         for (int ai = 0; ai < 2; ++ai)
; #pragma unroll
;             for (int m = 0; m < 4; ++m) { bf16_t* rowp = O + (size_t)(row0 + ai * HALF + m * 16) * ldc + col0;
;                 float h[8];
; #pragma unroll
;                 for (int n = 0; n < 2; ++n)
; #pragma unroll
;                     for (int j = 0; j < 4; ++j) { const float g = acc[ai][0][m][n][j], up = acc[ai][1][m][n][j];
;                         const float e = __builtin_amdgcn_exp2f(-1.4426950408889634f * g);
;                         h[n * 4 + j] = g * __builtin_amdgcn_rcpf(1.0f + e) * up; }
;                 u32x4 w; w.x = cvt_pk_bf16(h[0], h[1]); w.y = cvt_pk_bf16(h[2], h[3]); w.z = cvt_pk_bf16(h[4], h[5]); w.w = cvt_pk_bf16(h[6], h[7]);
;                 *(u32x4*)rowp = w; }
; template <class Epi, class Sched>
; __device__ __forceinline__ void gemm_phase(LAS unsigned char* lds, const Gemm g, const Sched& S, const Epi& E) {
;     ...
;             PG8_BAR; PG8_WAIT_L(0); PG8_MMA(1, 0, At, B0); PG8_BAR; PG8_SCHED;
;             PG8_STAGE(PG8_SB(1, 1), b3 + hstep, voffB);
;             PG8_WAIT_V(6); PG8_BAR; PG8_MMA(1, 1, At, B1); PG8_BAR;
;         }
	s_waitcnt lgkmcnt(0)
	s_waitcnt lgkmcnt(0)
	v_mfma_f32_16x16x32_bf16 v[60:63], v[144:147], v[172:175], v[60:63]
	v_mfma_f32_16x16x32_bf16 v[52:55], v[164:167], v[172:175], v[52:55]
	v_mfma_f32_16x16x32_bf16 v[44:47], v[144:147], v[204:207], v[44:47]
	v_mfma_f32_16x16x32_bf16 v[36:39], v[164:167], v[204:207], v[36:39]
	v_mfma_f32_16x16x32_bf16 v[28:31], v[144:147], v[212:215], v[28:31]
	v_mfma_f32_16x16x32_bf16 v[20:23], v[164:167], v[212:215], v[20:23]
	v_mfma_f32_16x16x32_bf16 v[12:15], v[144:147], v[220:223], v[12:15]
	v_mfma_f32_16x16x32_bf16 v[4:7], v[164:167], v[220:223], v[4:7]
	v_mfma_f32_16x16x32_bf16 v[60:63], v[160:163], v[200:203], v[60:63]
	v_mfma_f32_16x16x32_bf16 v[52:55], v[168:171], v[200:203], v[52:55]
	v_mfma_f32_16x16x32_bf16 v[44:47], v[160:163], v[208:211], v[44:47]
	v_mfma_f32_16x16x32_bf16 v[36:39], v[168:171], v[208:211], v[36:39]
	v_mfma_f32_16x16x32_bf16 v[28:31], v[160:163], v[216:219], v[28:31]
	v_mfma_f32_16x16x32_bf16 v[20:23], v[168:171], v[216:219], v[20:23]
	v_mfma_f32_16x16x32_bf16 v[12:15], v[160:163], v[224:227], v[12:15]
	v_mfma_f32_16x16x32_bf16 v[4:7], v[168:171], v[224:227], v[4:7]
	s_barrier
	s_add_u32 s20, s20, 0x80080
	s_addc_u32 s21, s21, 0
	s_add_i32 s22, s22, s29
	s_mov_b32 m0, s22
	s_nop 0
	global_load_lds_dwordx4 v148, s[20:21]
	s_add_i32 m0, s22, 0x2000
	s_nop 0
	global_load_lds_dwordx4 v128, s[20:21]
	s_waitcnt vmcnt(6)
	s_barrier
	v_mfma_f32_16x16x32_bf16 v[56:59], v[228:231], v[172:175], v[56:59]
	v_mfma_f32_16x16x32_bf16 v[48:51], v[236:239], v[172:175], v[48:51]
	v_mfma_f32_16x16x32_bf16 v[40:43], v[228:231], v[204:207], v[40:43]
	v_mfma_f32_16x16x32_bf16 v[32:35], v[236:239], v[204:207], v[32:35]
	v_mfma_f32_16x16x32_bf16 v[24:27], v[228:231], v[212:215], v[24:27]
	v_mfma_f32_16x16x32_bf16 v[16:19], v[236:239], v[212:215], v[16:19]
	v_mfma_f32_16x16x32_bf16 v[8:11], v[228:231], v[220:223], v[8:11]
	v_mfma_f32_16x16x32_bf16 v[0:3], v[236:239], v[220:223], v[0:3]
	v_mfma_f32_16x16x32_bf16 v[56:59], v[232:235], v[200:203], v[56:59]
	v_mfma_f32_16x16x32_bf16 v[48:51], v[240:243], v[200:203], v[48:51]
	v_mfma_f32_16x16x32_bf16 v[40:43], v[232:235], v[208:211], v[40:43]
	v_mfma_f32_16x16x32_bf16 v[32:35], v[240:243], v[208:211], v[32:35]
	v_mfma_f32_16x16x32_bf16 v[24:27], v[232:235], v[216:219], v[24:27]
	v_mfma_f32_16x16x32_bf16 v[16:19], v[240:243], v[216:219], v[16:19]
	v_mfma_f32_16x16x32_bf16 v[8:11], v[232:235], v[224:227], v[8:11]
	v_mfma_f32_16x16x32_bf16 v[0:3], v[240:243], v[224:227], v[0:3]
	s_add_i32 s44, s44, 2
	s_add_u32 s16, s16, 0x100
	s_addc_u32 s17, s17, 0
	s_add_u32 s42, s42, 0x100
	s_addc_u32 s43, s43, 0
	s_cmp_gt_u32 s44, 29
	s_barrier
	s_cbranch_scc0 .LBB0_213
	v_mul_f32_e32 v145, 0xbfb8aa3b, v124
	v_exp_f32_e32 v145, v145
	v_lshl_or_b32 v146, s38, 7, v142
	v_lshl_add_u32 v144, s39, 8, v140
	v_ashrrev_i32_e32 v147, 31, v146
	v_add_f32_e32 v145, 1.0, v145
	v_rcp_f32_e32 v145, v145
	v_mov_b64_e32 v[138:139], s[4:5]
	s_movk_i32 s7, 0x2c00
	v_mad_i64_i32 v[160:161], s[16:17], v144, s7, v[138:139]
	v_mul_f32_e32 v124, v124, v145
	v_mul_f32_e32 v120, v120, v124
	v_mul_f32_e32 v124, 0xbfb8aa3b, v125
	v_exp_f32_e32 v124, v124
	s_and_b64 vcc, exec, s[0:1]
	s_mov_b32 s38, s6
	s_mov_b32 s39, s10
	v_add_f32_e32 v124, 1.0, v124
	v_rcp_f32_e32 v124, v124
	s_mov_b64 s[20:21], s[14:15]
	v_mul_f32_e32 v124, v125, v124
	v_mul_f32_e32 v121, v121, v124
	v_mul_f32_e32 v124, 0xbfb8aa3b, v126
	v_exp_f32_e32 v124, v124
	s_nop 0
	v_add_f32_e32 v124, 1.0, v124
	v_rcp_f32_e32 v124, v124
	s_nop 0
	v_mul_f32_e32 v124, v126, v124
	v_mul_f32_e32 v122, v122, v124
	v_mul_f32_e32 v124, 0xbfb8aa3b, v127
	v_exp_f32_e32 v124, v124
	s_nop 0
	v_add_f32_e32 v124, 1.0, v124
	v_rcp_f32_e32 v124, v124
	s_nop 0
	v_mul_f32_e32 v124, v127, v124
	v_mul_f32_e32 v123, v123, v124
	v_mul_f32_e32 v124, 0xbfb8aa3b, v116
	v_exp_f32_e32 v124, v124
	s_nop 0
	v_add_f32_e32 v124, 1.0, v124
	v_rcp_f32_e32 v124, v124
	s_nop 0
	v_mul_f32_e32 v116, v116, v124
	v_mul_f32_e32 v116, v112, v116
	v_mul_f32_e32 v112, 0xbfb8aa3b, v117
	v_exp_f32_e32 v112, v112
	s_nop 0
	v_add_f32_e32 v112, 1.0, v112
	v_rcp_f32_e32 v112, v112
	s_nop 0
	v_mul_f32_e32 v112, v117, v112
	v_mul_f32_e32 v117, v113, v112
	v_mul_f32_e32 v112, 0xbfb8aa3b, v118
	v_exp_f32_e32 v112, v112
	v_cvt_pk_bf16_f32 v116, v116, v117
	s_nop 0
	v_add_f32_e32 v112, 1.0, v112
	v_rcp_f32_e32 v112, v112
	s_nop 0
	v_mul_f32_e32 v112, v118, v112
	v_mul_f32_e32 v124, v114, v112
	v_mul_f32_e32 v112, 0xbfb8aa3b, v119
	v_exp_f32_e32 v112, v112
	v_cvt_pk_bf16_f32 v114, v120, v121
	s_nop 0
	v_add_f32_e32 v112, 1.0, v112
	v_rcp_f32_e32 v112, v112
	s_nop 0
	v_mul_f32_e32 v112, v119, v112
	v_mul_f32_e32 v125, v115, v112
	v_lshlrev_b64 v[112:113], 1, v[146:147]
	v_lshl_add_u64 v[118:119], v[160:161], 0, v[112:113]
	v_cvt_pk_bf16_f32 v115, v122, v123
	v_cvt_pk_bf16_f32 v117, v124, v125
	global_store_dwordx4 v[118:119], v[114:117], off
	s_nop 1
	v_mul_f32_e32 v116, 0xbfb8aa3b, v108
	v_exp_f32_e32 v116, v116
	v_or_b32_e32 v114, 16, v144
	v_mad_i64_i32 v[114:115], s[16:17], v114, s7, v[138:139]
	v_add_f32_e32 v116, 1.0, v116
	v_rcp_f32_e32 v116, v116
	s_nop 0
	v_mul_f32_e32 v108, v108, v116
	v_mul_f32_e32 v104, v104, v108
	v_mul_f32_e32 v108, 0xbfb8aa3b, v109
	v_exp_f32_e32 v108, v108
	s_nop 0
	v_add_f32_e32 v108, 1.0, v108
	v_rcp_f32_e32 v108, v108
	s_nop 0
	v_mul_f32_e32 v108, v109, v108
	v_mul_f32_e32 v105, v105, v108
	v_mul_f32_e32 v108, 0xbfb8aa3b, v110
	v_exp_f32_e32 v108, v108
	s_nop 0
	v_add_f32_e32 v108, 1.0, v108
	v_rcp_f32_e32 v108, v108
	s_nop 0
	v_mul_f32_e32 v108, v110, v108
	v_mul_f32_e32 v106, v106, v108
	v_mul_f32_e32 v108, 0xbfb8aa3b, v111
	v_exp_f32_e32 v108, v108
	s_nop 0
; __device__ __forceinline__ unsigned cvt_pk_bf16(float lo, float hi) { unsigned r; asm("v_cvt_pk_bf16_f32 %0, %1, %2" : "=v"(r) : "v"(lo), "v"(hi)); return r; }
;     __device__ __forceinline__ void operator()(const f32x4 (&acc)[2][2][4][2], const Unit& u, int wr, int wc, int fr, int fq) const {
;         const int row0 = u.pm * BM + wr * 64 + fr, col0 = u.pn * HALF + wc * 32 + 8 * fq;
; #pragma unroll
;         for (int ai = 0; ai < 2; ++ai)
; #pragma unroll
;             for (int m = 0; m < 4; ++m) { bf16_t* rowp = O + (size_t)(row0 + ai * HALF + m * 16) * ldc + col0;
;                 float h[8];
; #pragma unroll
;                 for (int n = 0; n < 2; ++n)
; #pragma unroll
;                     for (int j = 0; j < 4; ++j) { const float g = acc[ai][0][m][n][j], up = acc[ai][1][m][n][j];
;                         const float e = __builtin_amdgcn_exp2f(-1.4426950408889634f * g);
;                         h[n * 4 + j] = g * __builtin_amdgcn_rcpf(1.0f + e) * up; }
;                 u32x4 w; w.x = cvt_pk_bf16(h[0], h[1]); w.y = cvt_pk_bf16(h[2], h[3]); w.z = cvt_pk_bf16(h[4], h[5]); w.w = cvt_pk_bf16(h[6], h[7]);
;                 *(u32x4*)rowp = w; }
	v_add_f32_e32 v108, 1.0, v108
	v_rcp_f32_e32 v108, v108
	s_nop 0
	v_mul_f32_e32 v108, v111, v108
	v_mul_f32_e32 v107, v107, v108
	v_mul_f32_e32 v108, 0xbfb8aa3b, v100
	v_exp_f32_e32 v108, v108
	s_nop 0
	v_add_f32_e32 v108, 1.0, v108
	v_rcp_f32_e32 v108, v108
	s_nop 0
	v_mul_f32_e32 v100, v100, v108
	v_mul_f32_e32 v108, v96, v100
	v_mul_f32_e32 v96, 0xbfb8aa3b, v101
	v_exp_f32_e32 v96, v96
	s_nop 0
	v_add_f32_e32 v96, 1.0, v96
	v_rcp_f32_e32 v96, v96
	s_nop 0
	v_mul_f32_e32 v96, v101, v96
	v_mul_f32_e32 v109, v97, v96
	v_mul_f32_e32 v96, 0xbfb8aa3b, v102
	v_exp_f32_e32 v96, v96
	v_lshl_add_u64 v[100:101], v[114:115], 0, v[112:113]
	v_cvt_pk_bf16_f32 v97, v106, v107
	v_add_f32_e32 v96, 1.0, v96
	v_rcp_f32_e32 v96, v96
	s_nop 0
	v_mul_f32_e32 v96, v102, v96
	v_mul_f32_e32 v102, v98, v96
	v_mul_f32_e32 v96, 0xbfb8aa3b, v103
	v_exp_f32_e32 v96, v96
	v_cvt_pk_bf16_f32 v98, v108, v109
	s_nop 0
	v_add_f32_e32 v96, 1.0, v96
	v_rcp_f32_e32 v96, v96
	s_nop 0
	v_mul_f32_e32 v96, v103, v96
	v_mul_f32_e32 v99, v99, v96
	v_cvt_pk_bf16_f32 v96, v104, v105
	v_cvt_pk_bf16_f32 v99, v102, v99
	global_store_dwordx4 v[100:101], v[96:99], off
	s_nop 1
	v_mul_f32_e32 v98, 0xbfb8aa3b, v92
	v_exp_f32_e32 v98, v98
	v_or_b32_e32 v96, 32, v144
	v_mad_i64_i32 v[96:97], s[16:17], v96, s7, v[138:139]
	v_add_f32_e32 v98, 1.0, v98
	v_rcp_f32_e32 v98, v98
	s_nop 0
	v_mul_f32_e32 v92, v92, v98
	v_mul_f32_e32 v88, v88, v92
	v_mul_f32_e32 v92, 0xbfb8aa3b, v93
	v_exp_f32_e32 v92, v92
	s_nop 0
	v_add_f32_e32 v92, 1.0, v92
	v_rcp_f32_e32 v92, v92
	s_nop 0
	v_mul_f32_e32 v92, v93, v92
	v_mul_f32_e32 v89, v89, v92
	v_mul_f32_e32 v92, 0xbfb8aa3b, v94
	v_exp_f32_e32 v92, v92
	s_nop 0
	v_add_f32_e32 v92, 1.0, v92
	v_rcp_f32_e32 v92, v92
	s_nop 0
	v_mul_f32_e32 v92, v94, v92
	v_mul_f32_e32 v90, v90, v92
	v_mul_f32_e32 v92, 0xbfb8aa3b, v95
	v_exp_f32_e32 v92, v92
	s_nop 0
	v_add_f32_e32 v92, 1.0, v92
	v_rcp_f32_e32 v92, v92
	s_nop 0
	v_mul_f32_e32 v92, v95, v92
	v_mul_f32_e32 v91, v91, v92
	v_mul_f32_e32 v92, 0xbfb8aa3b, v84
	v_exp_f32_e32 v92, v92
	s_nop 0
	v_add_f32_e32 v92, 1.0, v92
	v_rcp_f32_e32 v92, v92
	s_nop 0
	v_mul_f32_e32 v84, v84, v92
	v_mul_f32_e32 v92, v80, v84
	v_mul_f32_e32 v80, 0xbfb8aa3b, v85
	v_exp_f32_e32 v80, v80
	s_nop 0
	v_add_f32_e32 v80, 1.0, v80
	v_rcp_f32_e32 v80, v80
	s_nop 0
	v_mul_f32_e32 v80, v85, v80
	v_mul_f32_e32 v93, v81, v80
	v_mul_f32_e32 v80, 0xbfb8aa3b, v86
	v_exp_f32_e32 v80, v80
	v_lshl_add_u64 v[84:85], v[96:97], 0, v[112:113]
	v_cvt_pk_bf16_f32 v81, v90, v91
	v_add_f32_e32 v80, 1.0, v80
	v_rcp_f32_e32 v80, v80
	s_nop 0
	v_mul_f32_e32 v80, v86, v80
	v_mul_f32_e32 v86, v82, v80
	v_mul_f32_e32 v80, 0xbfb8aa3b, v87
	v_exp_f32_e32 v80, v80
	v_cvt_pk_bf16_f32 v82, v92, v93
	s_nop 0
	v_add_f32_e32 v80, 1.0, v80
	v_rcp_f32_e32 v80, v80
	s_nop 0
	v_mul_f32_e32 v80, v87, v80
	v_mul_f32_e32 v83, v83, v80
	v_cvt_pk_bf16_f32 v80, v88, v89
	v_cvt_pk_bf16_f32 v83, v86, v83
	global_store_dwordx4 v[84:85], v[80:83], off
	s_nop 1
	v_mul_f32_e32 v82, 0xbfb8aa3b, v76
	v_exp_f32_e32 v82, v82
	v_or_b32_e32 v80, 48, v144
	v_mad_i64_i32 v[80:81], s[16:17], v80, s7, v[138:139]
	v_add_f32_e32 v82, 1.0, v82
	v_rcp_f32_e32 v82, v82
	s_nop 0
	v_mul_f32_e32 v76, v76, v82
	v_mul_f32_e32 v72, v72, v76
	v_mul_f32_e32 v76, 0xbfb8aa3b, v77
	v_exp_f32_e32 v76, v76
	s_nop 0
	v_add_f32_e32 v76, 1.0, v76
	v_rcp_f32_e32 v76, v76
	s_nop 0
	v_mul_f32_e32 v76, v77, v76
	v_mul_f32_e32 v73, v73, v76
	v_mul_f32_e32 v76, 0xbfb8aa3b, v78
	v_exp_f32_e32 v76, v76
	s_nop 0
	v_add_f32_e32 v76, 1.0, v76
	v_rcp_f32_e32 v76, v76
	s_nop 0
	v_mul_f32_e32 v76, v78, v76
	v_mul_f32_e32 v74, v74, v76
	v_mul_f32_e32 v76, 0xbfb8aa3b, v79
	v_exp_f32_e32 v76, v76
	s_nop 0
	v_add_f32_e32 v76, 1.0, v76
	v_rcp_f32_e32 v76, v76
	s_nop 0
	v_mul_f32_e32 v76, v79, v76
	v_mul_f32_e32 v75, v75, v76
	v_mul_f32_e32 v76, 0xbfb8aa3b, v68
	v_exp_f32_e32 v76, v76
	s_nop 0
	v_add_f32_e32 v76, 1.0, v76
	v_rcp_f32_e32 v76, v76
	s_nop 0
	v_mul_f32_e32 v68, v68, v76
	v_mul_f32_e32 v76, v64, v68
	v_mul_f32_e32 v64, 0xbfb8aa3b, v69
	v_exp_f32_e32 v64, v64
	s_nop 0
	v_add_f32_e32 v64, 1.0, v64
	v_rcp_f32_e32 v64, v64
	s_nop 0
	v_mul_f32_e32 v64, v69, v64
	v_mul_f32_e32 v77, v65, v64
	v_mul_f32_e32 v64, 0xbfb8aa3b, v70
	v_exp_f32_e32 v64, v64
	v_lshl_add_u64 v[68:69], v[80:81], 0, v[112:113]
	v_cvt_pk_bf16_f32 v65, v74, v75
	v_add_f32_e32 v64, 1.0, v64
	v_rcp_f32_e32 v64, v64
	s_nop 0
	v_mul_f32_e32 v64, v70, v64
	v_mul_f32_e32 v70, v66, v64
	v_mul_f32_e32 v64, 0xbfb8aa3b, v71
	v_exp_f32_e32 v64, v64
	v_cvt_pk_bf16_f32 v66, v76, v77
	s_nop 0
	v_add_f32_e32 v64, 1.0, v64
	v_rcp_f32_e32 v64, v64
	s_nop 0
	v_mul_f32_e32 v64, v71, v64
	v_mul_f32_e32 v67, v67, v64
	v_cvt_pk_bf16_f32 v64, v72, v73
	v_cvt_pk_bf16_f32 v67, v70, v67
	global_store_dwordx4 v[68:69], v[64:67], off
	s_nop 1
	v_mul_f32_e32 v66, 0xbfb8aa3b, v60
	v_exp_f32_e32 v66, v66
	v_add_u32_e32 v64, 0x80, v144
	v_mad_i64_i32 v[64:65], s[16:17], v64, s7, v[138:139]
	v_add_f32_e32 v66, 1.0, v66
	v_rcp_f32_e32 v66, v66
	s_nop 0
	v_mul_f32_e32 v60, v60, v66
	v_mul_f32_e32 v56, v56, v60
	v_mul_f32_e32 v60, 0xbfb8aa3b, v61
	v_exp_f32_e32 v60, v60
	s_nop 0
	v_add_f32_e32 v60, 1.0, v60
	v_rcp_f32_e32 v60, v60
	s_nop 0
	v_mul_f32_e32 v60, v61, v60
	v_mul_f32_e32 v57, v57, v60
	v_mul_f32_e32 v60, 0xbfb8aa3b, v62
	v_exp_f32_e32 v60, v60
	s_nop 0
	v_add_f32_e32 v60, 1.0, v60
	v_rcp_f32_e32 v60, v60
	s_nop 0
	v_mul_f32_e32 v60, v62, v60
	v_mul_f32_e32 v58, v58, v60
	v_mul_f32_e32 v60, 0xbfb8aa3b, v63
	v_exp_f32_e32 v60, v60
	s_nop 0
	v_add_f32_e32 v60, 1.0, v60
	v_rcp_f32_e32 v60, v60
	s_nop 0
	v_mul_f32_e32 v60, v63, v60
	v_mul_f32_e32 v59, v59, v60
	v_mul_f32_e32 v60, 0xbfb8aa3b, v52
; __device__ __forceinline__ unsigned cvt_pk_bf16(float lo, float hi) { unsigned r; asm("v_cvt_pk_bf16_f32 %0, %1, %2" : "=v"(r) : "v"(lo), "v"(hi)); return r; }
; #define PG8_WAIT_V(n) asm volatile("s_waitcnt vmcnt(" #n ")" ::: "memory")
; #define PG8_BAR __builtin_amdgcn_s_barrier()
;     __device__ __forceinline__ void operator()(const f32x4 (&acc)[2][2][4][2], const Unit& u, int wr, int wc, int fr, int fq) const {
;         const int row0 = u.pm * BM + wr * 64 + fr, col0 = u.pn * HALF + wc * 32 + 8 * fq;
; #pragma unroll
;         for (int ai = 0; ai < 2; ++ai)
; #pragma unroll
;             for (int m = 0; m < 4; ++m) { bf16_t* rowp = O + (size_t)(row0 + ai * HALF + m * 16) * ldc + col0;
;                 float h[8];
; #pragma unroll
;                 for (int n = 0; n < 2; ++n)
; #pragma unroll
;                     for (int j = 0; j < 4; ++j) { const float g = acc[ai][0][m][n][j], up = acc[ai][1][m][n][j];
;                         const float e = __builtin_amdgcn_exp2f(-1.4426950408889634f * g);
;                         h[n * 4 + j] = g * __builtin_amdgcn_rcpf(1.0f + e) * up; }
;                 u32x4 w; w.x = cvt_pk_bf16(h[0], h[1]); w.y = cvt_pk_bf16(h[2], h[3]); w.z = cvt_pk_bf16(h[4], h[5]); w.w = cvt_pk_bf16(h[6], h[7]);
;                 *(u32x4*)rowp = w; }
; template <class Epi, class Sched>
; __device__ __forceinline__ void gemm_phase(LAS unsigned char* lds, const Gemm g, const Sched& S, const Epi& E) {
;     ...
;         E(acc, cur, wr, wc, fr, fq);
;         if (!has_next) break;
; #pragma unroll
;         for (int a = 0; a < 2; ++a)
; #pragma unroll
;             for (int b = 0; b < 2; ++b)
; #pragma unroll
;                 for (int m = 0; m < 4; ++m)
; #pragma unroll
;                     for (int n = 0; n < 2; ++n) acc[a][b][m][n] = (f32x4){0.f, 0.f, 0.f, 0.f};
;         cur = nxt; cA = nA; cB = nB; ++ui;
;     }
;     PG8_WAIT_V(0);
;     if (wr == 0) PG8_BAR;
	v_exp_f32_e32 v60, v60
	s_nop 0
	v_add_f32_e32 v60, 1.0, v60
	v_rcp_f32_e32 v60, v60
	s_nop 0
	v_mul_f32_e32 v52, v52, v60
	v_mul_f32_e32 v60, v48, v52
	v_mul_f32_e32 v48, 0xbfb8aa3b, v53
	v_exp_f32_e32 v48, v48
	s_nop 0
	v_add_f32_e32 v48, 1.0, v48
	v_rcp_f32_e32 v48, v48
	s_nop 0
	v_mul_f32_e32 v48, v53, v48
	v_mul_f32_e32 v61, v49, v48
	v_mul_f32_e32 v48, 0xbfb8aa3b, v54
	v_exp_f32_e32 v48, v48
	v_lshl_add_u64 v[52:53], v[64:65], 0, v[112:113]
	v_cvt_pk_bf16_f32 v49, v58, v59
	v_add_f32_e32 v48, 1.0, v48
	v_rcp_f32_e32 v48, v48
	s_nop 0
	v_mul_f32_e32 v48, v54, v48
	v_mul_f32_e32 v54, v50, v48
	v_mul_f32_e32 v48, 0xbfb8aa3b, v55
	v_exp_f32_e32 v48, v48
	v_cvt_pk_bf16_f32 v50, v60, v61
	s_nop 0
	v_add_f32_e32 v48, 1.0, v48
	v_rcp_f32_e32 v48, v48
	s_nop 0
	v_mul_f32_e32 v48, v55, v48
	v_mul_f32_e32 v51, v51, v48
	v_cvt_pk_bf16_f32 v48, v56, v57
	v_cvt_pk_bf16_f32 v51, v54, v51
	global_store_dwordx4 v[52:53], v[48:51], off
	s_nop 1
	v_mul_f32_e32 v50, 0xbfb8aa3b, v44
	v_exp_f32_e32 v50, v50
	v_add_u32_e32 v48, 0x90, v144
	v_mad_i64_i32 v[48:49], s[16:17], v48, s7, v[138:139]
	v_add_f32_e32 v50, 1.0, v50
	v_rcp_f32_e32 v50, v50
	s_nop 0
	v_mul_f32_e32 v44, v44, v50
	v_mul_f32_e32 v40, v40, v44
	v_mul_f32_e32 v44, 0xbfb8aa3b, v45
	v_exp_f32_e32 v44, v44
	s_nop 0
	v_add_f32_e32 v44, 1.0, v44
	v_rcp_f32_e32 v44, v44
	s_nop 0
	v_mul_f32_e32 v44, v45, v44
	v_mul_f32_e32 v41, v41, v44
	v_mul_f32_e32 v44, 0xbfb8aa3b, v46
	v_exp_f32_e32 v44, v44
	s_nop 0
	v_add_f32_e32 v44, 1.0, v44
	v_rcp_f32_e32 v44, v44
	s_nop 0
	v_mul_f32_e32 v44, v46, v44
	v_mul_f32_e32 v42, v42, v44
	v_mul_f32_e32 v44, 0xbfb8aa3b, v47
	v_exp_f32_e32 v44, v44
	s_nop 0
	v_add_f32_e32 v44, 1.0, v44
	v_rcp_f32_e32 v44, v44
	s_nop 0
	v_mul_f32_e32 v44, v47, v44
	v_mul_f32_e32 v43, v43, v44
	v_mul_f32_e32 v44, 0xbfb8aa3b, v36
	v_exp_f32_e32 v44, v44
	s_nop 0
	v_add_f32_e32 v44, 1.0, v44
	v_rcp_f32_e32 v44, v44
	s_nop 0
	v_mul_f32_e32 v36, v36, v44
	v_mul_f32_e32 v44, v32, v36
	v_mul_f32_e32 v32, 0xbfb8aa3b, v37
	v_exp_f32_e32 v32, v32
	s_nop 0
	v_add_f32_e32 v32, 1.0, v32
	v_rcp_f32_e32 v32, v32
	s_nop 0
	v_mul_f32_e32 v32, v37, v32
	v_mul_f32_e32 v45, v33, v32
	v_mul_f32_e32 v32, 0xbfb8aa3b, v38
	v_exp_f32_e32 v32, v32
	v_lshl_add_u64 v[36:37], v[48:49], 0, v[112:113]
	v_cvt_pk_bf16_f32 v33, v42, v43
	v_add_f32_e32 v32, 1.0, v32
	v_rcp_f32_e32 v32, v32
	s_nop 0
	v_mul_f32_e32 v32, v38, v32
	v_mul_f32_e32 v38, v34, v32
	v_mul_f32_e32 v32, 0xbfb8aa3b, v39
	v_exp_f32_e32 v32, v32
	v_cvt_pk_bf16_f32 v34, v44, v45
	s_nop 0
	v_add_f32_e32 v32, 1.0, v32
	v_rcp_f32_e32 v32, v32
	s_nop 0
	v_mul_f32_e32 v32, v39, v32
	v_mul_f32_e32 v35, v35, v32
	v_cvt_pk_bf16_f32 v32, v40, v41
	v_cvt_pk_bf16_f32 v35, v38, v35
	global_store_dwordx4 v[36:37], v[32:35], off
	s_nop 1
	v_mul_f32_e32 v34, 0xbfb8aa3b, v28
	v_exp_f32_e32 v34, v34
	v_add_u32_e32 v32, 0xa0, v144
	v_mad_i64_i32 v[32:33], s[16:17], v32, s7, v[138:139]
	v_add_f32_e32 v34, 1.0, v34
	v_rcp_f32_e32 v34, v34
	s_nop 0
	v_mul_f32_e32 v28, v28, v34
	v_mul_f32_e32 v24, v24, v28
	v_mul_f32_e32 v28, 0xbfb8aa3b, v29
	v_exp_f32_e32 v28, v28
	s_nop 0
	v_add_f32_e32 v28, 1.0, v28
	v_rcp_f32_e32 v28, v28
	s_nop 0
	v_mul_f32_e32 v28, v29, v28
	v_mul_f32_e32 v25, v25, v28
	v_mul_f32_e32 v28, 0xbfb8aa3b, v30
	v_exp_f32_e32 v28, v28
	s_nop 0
	v_add_f32_e32 v28, 1.0, v28
	v_rcp_f32_e32 v28, v28
	s_nop 0
	v_mul_f32_e32 v28, v30, v28
	v_mul_f32_e32 v26, v26, v28
	v_mul_f32_e32 v28, 0xbfb8aa3b, v31
	v_exp_f32_e32 v28, v28
	s_nop 0
	v_add_f32_e32 v28, 1.0, v28
	v_rcp_f32_e32 v28, v28
	s_nop 0
	v_mul_f32_e32 v28, v31, v28
	v_mul_f32_e32 v27, v27, v28
	v_mul_f32_e32 v28, 0xbfb8aa3b, v20
	v_exp_f32_e32 v28, v28
	s_nop 0
	v_add_f32_e32 v28, 1.0, v28
	v_rcp_f32_e32 v28, v28
	s_nop 0
	v_mul_f32_e32 v20, v20, v28
	v_mul_f32_e32 v28, v16, v20
	v_mul_f32_e32 v16, 0xbfb8aa3b, v21
	v_exp_f32_e32 v16, v16
	s_nop 0
	v_add_f32_e32 v16, 1.0, v16
	v_rcp_f32_e32 v16, v16
	s_nop 0
	v_mul_f32_e32 v16, v21, v16
	v_mul_f32_e32 v29, v17, v16
	v_mul_f32_e32 v16, 0xbfb8aa3b, v22
	v_exp_f32_e32 v16, v16
	v_lshl_add_u64 v[20:21], v[32:33], 0, v[112:113]
	v_cvt_pk_bf16_f32 v17, v26, v27
	v_add_f32_e32 v16, 1.0, v16
	v_rcp_f32_e32 v16, v16
	s_nop 0
	v_mul_f32_e32 v16, v22, v16
	v_mul_f32_e32 v22, v18, v16
	v_mul_f32_e32 v16, 0xbfb8aa3b, v23
	v_exp_f32_e32 v16, v16
	v_cvt_pk_bf16_f32 v18, v28, v29
	s_nop 0
	v_add_f32_e32 v16, 1.0, v16
	v_rcp_f32_e32 v16, v16
	s_nop 0
	v_mul_f32_e32 v16, v23, v16
	v_mul_f32_e32 v19, v19, v16
	v_cvt_pk_bf16_f32 v16, v24, v25
	v_cvt_pk_bf16_f32 v19, v22, v19
	global_store_dwordx4 v[20:21], v[16:19], off
	s_nop 1
	v_mul_f32_e32 v18, 0xbfb8aa3b, v12
	v_exp_f32_e32 v18, v18
	v_add_u32_e32 v16, 0xb0, v144
	v_mad_i64_i32 v[16:17], s[16:17], v16, s7, v[138:139]
	v_add_f32_e32 v18, 1.0, v18
	v_rcp_f32_e32 v18, v18
	s_mov_b64 s[16:17], s[12:13]
	v_mul_f32_e32 v12, v12, v18
	v_mul_f32_e32 v8, v8, v12
	v_mul_f32_e32 v12, 0xbfb8aa3b, v13
	v_exp_f32_e32 v12, v12
	s_nop 0
	v_add_f32_e32 v12, 1.0, v12
	v_rcp_f32_e32 v12, v12
	s_nop 0
	v_mul_f32_e32 v12, v13, v12
	v_mul_f32_e32 v9, v9, v12
	v_mul_f32_e32 v12, 0xbfb8aa3b, v14
	v_exp_f32_e32 v12, v12
	s_nop 0
	v_add_f32_e32 v12, 1.0, v12
	v_rcp_f32_e32 v12, v12
	s_nop 0
	v_mul_f32_e32 v12, v14, v12
	v_mul_f32_e32 v10, v10, v12
	v_mul_f32_e32 v12, 0xbfb8aa3b, v15
	v_exp_f32_e32 v12, v12
	s_nop 0
	v_add_f32_e32 v12, 1.0, v12
	v_rcp_f32_e32 v12, v12
	s_nop 0
	v_mul_f32_e32 v12, v15, v12
	v_mul_f32_e32 v11, v11, v12
	v_mul_f32_e32 v12, 0xbfb8aa3b, v4
	v_exp_f32_e32 v12, v12
	s_nop 0
	v_add_f32_e32 v12, 1.0, v12
	v_rcp_f32_e32 v12, v12
	s_nop 0
	v_mul_f32_e32 v4, v4, v12
	v_mul_f32_e32 v12, v0, v4
	v_mul_f32_e32 v0, 0xbfb8aa3b, v5
	v_exp_f32_e32 v0, v0
	s_nop 0
	v_add_f32_e32 v0, 1.0, v0
	v_rcp_f32_e32 v0, v0
	s_nop 0
	v_mul_f32_e32 v0, v5, v0
	v_mul_f32_e32 v13, v1, v0
	v_mul_f32_e32 v0, 0xbfb8aa3b, v6
	v_exp_f32_e32 v0, v0
	v_lshl_add_u64 v[4:5], v[16:17], 0, v[112:113]
	v_cvt_pk_bf16_f32 v1, v10, v11
	v_add_f32_e32 v0, 1.0, v0
	v_rcp_f32_e32 v0, v0
	s_nop 0
	v_mul_f32_e32 v0, v6, v0
	v_mul_f32_e32 v6, v2, v0
	v_mul_f32_e32 v0, 0xbfb8aa3b, v7
	v_exp_f32_e32 v0, v0
	v_cvt_pk_bf16_f32 v2, v12, v13
	s_nop 0
	v_add_f32_e32 v0, 1.0, v0
	v_rcp_f32_e32 v0, v0
	s_nop 0
	v_mul_f32_e32 v0, v7, v0
	v_mul_f32_e32 v3, v3, v0
	v_cvt_pk_bf16_f32 v0, v8, v9
	v_cvt_pk_bf16_f32 v3, v6, v3
	global_store_dwordx4 v[4:5], v[0:3], off
	s_cbranch_vccz .LBB0_210
	s_waitcnt vmcnt(0)
	s_cmpk_gt_u32 s24, 0xff
	s_cbranch_scc1 .LBB0_217
	s_barrier
